# v33_scanprio
# speedup vs baseline: 1.0022x; 1.0022x over previous
; #define LAS __attribute__((address_space(3)))
; __device__ __forceinline__ void phase_scan(const Params& p, LAS unsigned char* lds, int wave, int lane, int G) {
;     if (wave >= 2) return;
;     unsigned char* ws = p.ws;
;     const bf16_t* PROJ = (const bf16_t*)(ws + WS_SB); bf16_t* YG = (bf16_t*)(ws + WS_SC);
;     const float* Aw = (const float*)(ws + WS_SSM_A); const bf16_t* BB = (const bf16_t*)(ws + WS_SSM_BB); const bf16_t* Cm = (const bf16_t*)(ws + WS_SSM_C);
;     LAS float* BuL = (LAS float*)(lds + wave * 25600);
;     LAS unsigned char* SLb = lds + wave * 25600 + 16896;
;     const int r16 = lane & 15, kq = lane >> 4;
;     const bf16x8 zero8 = {0, 0, 0, 0, 0, 0, 0, 0};
;     for (int pair = blockIdx.x * 2 + wave; pair < 4 * NGRP; pair += G * 2) {
;         const int b = pair >> 7, g = pair & 127;
;         bf16x8 bfr[8], cfr[4];
; #pragma unroll
;         for (int n = 0; n < 8; ++n) { bfr[n] = zero8; if (kq < 2) bfr[n] = *(const bf16x8*)(BB + ((size_t)g * 128 + n * 16 + r16) * 16 + 8 * kq); }
; #pragma unroll
;         for (int ks = 0; ks < 4; ++ks) cfr[ks] = *(const bf16x8*)(Cm + ((size_t)g * 16 + r16) * 128 + 32 * ks + 8 * kq);
;         const float a_re = Aw[(g * 64 + lane) * 2], a_im = Aw[(g * 64 + lane) * 2 + 1];
;         const f32x4 dv = *(const f32x4*)(p.in[10] + g * 16 + 4 * kq);
;         float s_re = 0.f, s_im = 0.f;
;         const bf16_t* ub = PROJ + (size_t)(b * SEQ) * DIN + g * 16;
;         bf16_t* yb = YG + (size_t)(b * SEQ) * DSS + g * 16 + 4 * kq;
;         for (int ch = 0; ch < SEQ / 32; ++ch) {
.LBB0_267:
	s_load_dwordx16 s[16:31], s[0:1], 0x80
	s_cmp_lt_i32 s96, 3
	s_cselect_b64 s[0:1], -1, 0
	s_and_b64 s[6:7], s[0:1], s[4:5]
	s_andn2_b64 vcc, exec, s[6:7]
	s_cbranch_vccnz .LBB0_335
	s_cmpk_lt_u32 s78, 0x80
	s_mov_b64 s[0:1], -1
	s_cbranch_scc0 .LBB0_297
	s_lshl_b32 s9, s2, 1
	v_readlane_b32 s0, v255, 3
	s_or_b32 s3, s0, s9
	s_cmpk_gt_i32 s3, 0x1ff
	s_cbranch_scc1 .LBB0_296
	s_setprio 3
	v_and_b32_e32 v10, 63, v254
	v_lshrrev_b32_e32 v0, 1, v10
	v_and_b32_e32 v60, 48, v10
	v_mov_b32_e32 v61, 0
	v_readlane_b32 s35, v255, 3
	v_and_b32_e32 v3, 24, v0
	v_lshl_add_u64 v[0:1], s[58:59], 0, v[60:61]
	s_mov_b64 s[36:37], 0x14000
	s_add_u32 s10, s58, 0x4000
	s_mul_i32 s0, s35, 0x6400
	v_lshl_add_u64 v[62:63], v[0:1], 0, s[36:37]
	s_mov_b64 s[36:37], 0x94000
	s_addc_u32 s11, s59, 0
	v_and_b32_e32 v2, 15, v254
	s_add_i32 s14, s0, 0
	v_lshl_add_u64 v[64:65], v[0:1], 0, s[36:37]
	v_lshlrev_b32_e32 v1, 4, v10
	v_cmp_gt_u32_e64 s[0:1], 32, v10
	v_cmp_lt_u32_e64 s[4:5], 31, v10
	v_lshlrev_b32_e32 v92, 7, v2
	v_lshlrev_b32_e32 v4, 1, v10
	v_add_u32_e32 v5, s14, v60
	v_lshlrev_b32_e32 v6, 3, v10
	v_lshlrev_b32_e32 v7, 2, v10
	v_and_b32_e32 v0, 48, v254
	v_lshlrev_b32_e32 v93, 4, v2
	v_or_b32_e32 v9, 0x100, v1
	v_or_b32_e32 v10, 0x300, v1
	v_or_b32_e32 v94, 0x500, v1
	v_mul_u32_u24_e32 v11, 0x210, v2
	v_mul_u32_u24_e32 v12, 0x110, v2
	v_lshl_add_u64 v[66:67], s[40:41], 0, v[60:61]
	v_or_b32_e32 v95, 0x700, v1
	v_lshl_or_b32 v60, v2, 12, v3
	v_mul_hi_u32_u24_e32 v1, 0x6000, v2
	v_mul_u32_u24_e32 v2, 0x6000, v2
	v_add_u32_e32 v8, s14, v0
	v_readlane_b32 s36, v255, 0
	v_or_b32_e32 v0, v2, v0
	v_readlane_b32 s37, v255, 1
	s_add_i32 s9, s9, s35
	s_lshl_b32 s33, s2, 5
	s_lshl_b32 s35, s35, 4
	v_lshl_add_u64 v[70:71], s[58:59], 0, v[0:1]
	v_or_b32_e32 v0, v2, v3
	s_mov_b32 s15, 0
	s_lshl_b32 s8, s36, 1
	v_lshl_add_u64 v[68:69], s[58:59], 0, v[60:61]
	s_add_i32 s33, s33, s35
	s_lshl_b32 s35, s36, 5
	v_lshl_add_u64 v[72:73], s[58:59], 0, v[0:1]
	v_lshlrev_b32_e32 v96, 1, v93
	v_lshlrev_b32_e32 v97, 1, v9
	v_lshlrev_b32_e32 v98, 1, v10
	v_lshlrev_b32_e32 v99, 2, v4
	v_add_u32_e32 v100, v5, v11
	v_add_u32_e32 v101, s14, v6
	v_add_u32_e32 v102, s14, v7
	v_add_u32_e32 v103, v8, v12
	s_mov_b32 s61, 0x2b114000
	s_mov_b64 s[36:37], 0x20000
	s_mov_b64 s[38:39], 0xc0000
	v_mov_b32_e32 v104, 0x6000
	s_branch .LBB0_272

; #define LAS __attribute__((address_space(3)))
; __device__ __forceinline__ void phase_scan(const Params& p, LAS unsigned char* lds, int wave, int lane, int G) {
;     if (wave >= 2) return;
;     unsigned char* ws = p.ws;
;     const bf16_t* PROJ = (const bf16_t*)(ws + WS_SB); bf16_t* YG = (bf16_t*)(ws + WS_SC);
;     const float* Aw = (const float*)(ws + WS_SSM_A); const bf16_t* BB = (const bf16_t*)(ws + WS_SSM_BB); const bf16_t* Cm = (const bf16_t*)(ws + WS_SSM_C);
;     LAS float* BuL = (LAS float*)(lds + wave * 25600);
;     LAS unsigned char* SLb = lds + wave * 25600 + 16896;
;     const int r16 = lane & 15, kq = lane >> 4;
;     const bf16x8 zero8 = {0, 0, 0, 0, 0, 0, 0, 0};
;     for (int pair = blockIdx.x * 2 + wave; pair < 4 * NGRP; pair += G * 2) {
.LBB0_296:
	s_setprio 0
	s_mov_b64 s[0:1], 0
